# q/k RoPE epilogue hand-written: rotation in f32 (same op order), wave-private LDS image [map][token][64], full 128-byte row stores, running k-norm bound
# speedup vs baseline: 1.0077x; 1.0029x over previous
; DI int crow(int reg, int g) { return (reg & 3) + 8 * (reg >> 2) + 4 * g; }
; template <bool TR>
; DI void gemm_in_tile(const P& p, int l, int id, char* smem) {
;     ...
;   } else if (nt < 12) {
;     const bool isq = nt < 10;
;     const int h = (nt & 1) * 2 + wc;
;     u16* dst = isq ? p.Qb : p.Kb;
;     const float qs = isq ? (0.125f * 1.4426950408889634f) : 1.0f;
;     float kl0 = 0.f, kl1 = 0.f;
; #pragma unroll
;     for (int rb = 0; rb < 2; ++rb) {
; #pragma unroll
;       for (int reg = 0; reg < 16; ++reg) {
;         if ((reg & 7) == 0) asm volatile("" ::: "memory");
;         const int rl = 64 * wr + 32 * rb + crow(reg, g);
;         const int tok = m0 + rl;
;         const float rs = rs_s[rl] * qs;
;         const int pos = tok & 8191, b = tok >> 13;
;         const float2 cs = p.rope[pos * 32 + li];
.LBB0_332:
	s_andn2_b64 vcc, exec, s[8:9]
	s_cbranch_vccnz .LBB0_337
	v_add_u32_e32 v136, s76, v144
	v_and_b32_e32 v140, 0x1fc4, v136
	v_lshlrev_b32_e32 v137, 3, v177
	v_mov_b32_e32 v250, v144
	v_add_u32_e32 v250, s76, v250
	v_and_b32_e32 v250, 0x1fff, v250
	v_lshl_or_b32 v250, v250, 8, v137
	global_load_dwordx2 v[146:147], v250, s[50:51]
	v_or_b32_e32 v250, 1, v144
	v_add_u32_e32 v250, s76, v250
	v_and_b32_e32 v250, 0x1fff, v250
	v_lshl_or_b32 v250, v250, 8, v137
	global_load_dwordx2 v[148:149], v250, s[50:51]
	v_or_b32_e32 v250, 2, v144
	v_add_u32_e32 v250, s76, v250
	v_and_b32_e32 v250, 0x1fff, v250
	v_lshl_or_b32 v250, v250, 8, v137
	global_load_dwordx2 v[150:151], v250, s[50:51]
	v_or_b32_e32 v250, 3, v144
	v_add_u32_e32 v250, s76, v250
	v_and_b32_e32 v250, 0x1fff, v250
	v_lshl_or_b32 v250, v250, 8, v137
	global_load_dwordx2 v[152:153], v250, s[50:51]
	v_or_b32_e32 v250, 8, v144
	v_add_u32_e32 v250, s76, v250
	v_and_b32_e32 v250, 0x1fff, v250
	v_lshl_or_b32 v250, v250, 8, v137
	global_load_dwordx2 v[154:155], v250, s[50:51]
	v_or_b32_e32 v250, 9, v144
	v_add_u32_e32 v250, s76, v250
	v_and_b32_e32 v250, 0x1fff, v250
	v_lshl_or_b32 v250, v250, 8, v137
	global_load_dwordx2 v[156:157], v250, s[50:51]
	v_or_b32_e32 v250, 10, v144
	v_add_u32_e32 v250, s76, v250
	v_and_b32_e32 v250, 0x1fff, v250
	v_lshl_or_b32 v250, v250, 8, v137
	global_load_dwordx2 v[158:159], v250, s[50:51]
	v_or_b32_e32 v250, 11, v144
	v_add_u32_e32 v250, s76, v250
	v_and_b32_e32 v250, 0x1fff, v250
	v_lshl_or_b32 v250, v250, 8, v137
	global_load_dwordx2 v[160:161], v250, s[50:51]
	v_or_b32_e32 v250, 16, v144
	v_add_u32_e32 v250, s76, v250
	v_and_b32_e32 v250, 0x1fff, v250
	v_lshl_or_b32 v250, v250, 8, v137
	global_load_dwordx2 v[162:163], v250, s[50:51]
	v_or_b32_e32 v250, 17, v144
	v_add_u32_e32 v250, s76, v250
	v_and_b32_e32 v250, 0x1fff, v250
	v_lshl_or_b32 v250, v250, 8, v137
	global_load_dwordx2 v[164:165], v250, s[50:51]
	v_or_b32_e32 v250, 18, v144
	v_add_u32_e32 v250, s76, v250
	v_and_b32_e32 v250, 0x1fff, v250
	v_lshl_or_b32 v250, v250, 8, v137
	global_load_dwordx2 v[166:167], v250, s[50:51]
	v_or_b32_e32 v250, 19, v144
	v_add_u32_e32 v250, s76, v250
	v_and_b32_e32 v250, 0x1fff, v250
	v_lshl_or_b32 v250, v250, 8, v137
	global_load_dwordx2 v[168:169], v250, s[50:51]
	v_or_b32_e32 v250, 24, v144
	v_add_u32_e32 v250, s76, v250
	v_and_b32_e32 v250, 0x1fff, v250
	v_lshl_or_b32 v250, v250, 8, v137
	global_load_dwordx2 v[170:171], v250, s[50:51]
	v_or_b32_e32 v250, 25, v144
	v_add_u32_e32 v250, s76, v250
	v_and_b32_e32 v250, 0x1fff, v250
	v_lshl_or_b32 v250, v250, 8, v137
	global_load_dwordx2 v[172:173], v250, s[50:51]
	v_or_b32_e32 v250, 26, v144
	v_add_u32_e32 v250, s76, v250
	v_and_b32_e32 v250, 0x1fff, v250
	v_lshl_or_b32 v250, v250, 8, v137
	global_load_dwordx2 v[174:175], v250, s[50:51]
	v_or_b32_e32 v250, 27, v144
	v_add_u32_e32 v250, s76, v250
	v_and_b32_e32 v250, 0x1fff, v250
	v_lshl_or_b32 v250, v250, 8, v137
	global_load_dwordx2 v[220:221], v250, s[50:51]
	v_or_b32_e32 v250, 32, v144
	v_add_u32_e32 v250, s76, v250
	v_and_b32_e32 v250, 0x1fff, v250
	v_lshl_or_b32 v250, v250, 8, v137
	global_load_dwordx2 v[222:223], v250, s[50:51]
	v_or_b32_e32 v250, 33, v144
	v_add_u32_e32 v250, s76, v250
	v_and_b32_e32 v250, 0x1fff, v250
	v_lshl_or_b32 v250, v250, 8, v137
	global_load_dwordx2 v[224:225], v250, s[50:51]
	v_or_b32_e32 v250, 34, v144
	v_add_u32_e32 v250, s76, v250
	v_and_b32_e32 v250, 0x1fff, v250
	v_lshl_or_b32 v250, v250, 8, v137
	global_load_dwordx2 v[226:227], v250, s[50:51]
	v_or_b32_e32 v250, 35, v144
	v_add_u32_e32 v250, s76, v250
	v_and_b32_e32 v250, 0x1fff, v250
	v_lshl_or_b32 v250, v250, 8, v137
	global_load_dwordx2 v[228:229], v250, s[50:51]
	v_or_b32_e32 v250, 40, v144
	v_add_u32_e32 v250, s76, v250
	v_and_b32_e32 v250, 0x1fff, v250
	v_lshl_or_b32 v250, v250, 8, v137
	global_load_dwordx2 v[230:231], v250, s[50:51]
	v_or_b32_e32 v250, 41, v144
	v_add_u32_e32 v250, s76, v250
	v_and_b32_e32 v250, 0x1fff, v250
	v_lshl_or_b32 v250, v250, 8, v137
	global_load_dwordx2 v[232:233], v250, s[50:51]
	v_or_b32_e32 v250, 42, v144
	v_add_u32_e32 v250, s76, v250
	v_and_b32_e32 v250, 0x1fff, v250
	v_lshl_or_b32 v250, v250, 8, v137
	global_load_dwordx2 v[234:235], v250, s[50:51]
	v_or_b32_e32 v250, 43, v144
	v_add_u32_e32 v250, s76, v250
	v_and_b32_e32 v250, 0x1fff, v250
	v_lshl_or_b32 v250, v250, 8, v137
	global_load_dwordx2 v[236:237], v250, s[50:51]
	v_or_b32_e32 v250, 48, v144
	v_add_u32_e32 v250, s76, v250
	v_and_b32_e32 v250, 0x1fff, v250
	v_lshl_or_b32 v250, v250, 8, v137
	global_load_dwordx2 v[238:239], v250, s[50:51]
	v_or_b32_e32 v250, 49, v144
	v_add_u32_e32 v250, s76, v250
	v_and_b32_e32 v250, 0x1fff, v250
	v_lshl_or_b32 v250, v250, 8, v137
	global_load_dwordx2 v[240:241], v250, s[50:51]
	v_or_b32_e32 v250, 50, v144
	v_add_u32_e32 v250, s76, v250
	v_and_b32_e32 v250, 0x1fff, v250
	v_lshl_or_b32 v250, v250, 8, v137
	global_load_dwordx2 v[242:243], v250, s[50:51]
	v_or_b32_e32 v250, 51, v144
	v_add_u32_e32 v250, s76, v250
	v_and_b32_e32 v250, 0x1fff, v250
	v_lshl_or_b32 v250, v250, 8, v137
	global_load_dwordx2 v[244:245], v250, s[50:51]
	v_or_b32_e32 v250, 56, v144
	v_add_u32_e32 v250, s76, v250
	v_and_b32_e32 v250, 0x1fff, v250
	v_lshl_or_b32 v250, v250, 8, v137
	global_load_dwordx2 v[246:247], v250, s[50:51]
	v_or_b32_e32 v250, 57, v144
	v_add_u32_e32 v250, s76, v250
	v_and_b32_e32 v250, 0x1fff, v250
	v_lshl_or_b32 v250, v250, 8, v137
	global_load_dwordx2 v[190:191], v250, s[50:51]
	v_or_b32_e32 v250, 58, v144
	v_add_u32_e32 v250, s76, v250
	v_and_b32_e32 v250, 0x1fff, v250
	v_lshl_or_b32 v250, v250, 8, v137
	global_load_dwordx2 v[192:193], v250, s[50:51]
	v_or_b32_e32 v250, 59, v144
	v_add_u32_e32 v250, s76, v250
	v_and_b32_e32 v250, 0x1fff, v250
	v_lshl_or_b32 v250, v250, 8, v137
	global_load_dwordx2 v[194:195], v250, s[50:51]
	s_cmp_lt_u32 s74, 10
	s_cselect_b64 vcc, -1, 0
	s_lshl_b32 s8, s77, 1
	v_and_or_b32 v134, s8, 2, v145
	s_and_b64 s[8:9], vcc, exec
	s_cselect_b32 s9, s41, s43
	s_cselect_b32 s8, s40, s42
	s_mov_b64 s[98:99], s[8:9]
	s_add_i32 s8, 0, 0x24000
	v_cndmask_b32_e32 v135, 1.0, v216, vcc
	v_lshrrev_b32_e32 v141, 11, v136
	s_mov_b32 s9, 0x3fffc
	v_and_or_b32 v141, v141, s9, v134
	v_lshl_or_b32 v140, v141, 14, v140
	s_and_b64 vcc, vcc, exec
	v_lshl_add_u32 v196, v144, 2, s8
	v_and_b32_e32 v197, 63, v198
	v_lshrrev_b32_e32 v251, 6, v198
	v_lshlrev_b32_e32 v251, 14, v251
	v_lshrrev_b32_e32 v136, 5, v197
	v_lshlrev_b32_e32 v136, 9, v136
	v_and_b32_e32 v137, 31, v197
	v_lshl_add_u32 v136, v137, 1, v136
	v_add_u32_e32 v144, v136, v251
	v_lshrrev_b32_e32 v136, 3, v197
	v_and_b32_e32 v137, 7, v197
	v_lshlrev_b32_e32 v141, 7, v136
	v_lshl_add_u32 v141, v137, 4, v141
	v_add_u32_e32 v145, v141, v251
	v_and_b32_e32 v140, 0xfffffffb, v140
	v_add_u32_e32 v140, v140, v136
	v_lshlrev_b32_e32 v140, 7, v140
	v_lshl_add_u32 v249, v137, 4, v140
	v_mov_b32_e32 v250, 0
	v_mov_b32_e32 v251, 0
	ds_read_b128 v[128:131], v196 offset:0
	s_waitcnt lgkmcnt(0)
; DI u16 f2bf(float a) { return (u16)(pack2(a, 0.f) & 0xffffu); }
; DI int crow(int reg, int g) { return (reg & 3) + 8 * (reg >> 2) + 4 * g; }
; template <bool TR>
; DI void gemm_in_tile(const P& p, int l, int id, char* smem) {
;     ...
;         const int rl = 64 * wr + 32 * rb + crow(reg, g);
;         const int tok = m0 + rl;
;         const float rs = rs_s[rl] * qs;
;         const int pos = tok & 8191, b = tok >> 13;
;         const float2 cs = p.rope[pos * 32 + li];
; #pragma unroll
;         for (int c = 0; c < 2; ++c) {
;           const float x1 = acc[rb][2 * c][reg] * rs, x2 = acc[rb][2 * c + 1][reg] * rs;
;           const float o1 = x1 * cs.x - x2 * cs.y, o2 = x2 * cs.x + x1 * cs.y;
;           const size_t base = ((size_t)(((b * 4 + h) * 2 + c) * SEQ + pos)) * 64;
;           dst[base + li] = f2bf(o1);
;           dst[base + 32 + li] = f2bf(o2);
;           if (c == 0) kl0 = fmaxf(kl0, o1 * o1 + o2 * o2); else kl1 = fmaxf(kl1, o1 * o1 + o2 * o2);
	v_mul_f32_e32 v128, v135, v128
	v_mul_f32_e32 v129, v135, v129
	v_mul_f32_e32 v130, v135, v130
	v_mul_f32_e32 v131, v135, v131
	s_waitcnt vmcnt(0)
	v_mul_f32_e32 v112, v112, v128
	v_mul_f32_e32 v96, v96, v128
	v_mul_f32_e32 v136, v147, v96
	v_fma_f32 v136, v146, v112, -v136
	v_mul_f32_e32 v137, v146, v96
	v_fmac_f32_e32 v137, v147, v112
	v_cvt_pk_bf16_f32 v141, v136, v137
	ds_write_b16 v144, v141 offset:0
	ds_write_b16_d16_hi v144, v141 offset:64
	v_mul_f32_e32 v140, v136, v136
	v_fmac_f32_e32 v140, v137, v137
	v_max_f32_e32 v250, v250, v140
	v_mul_f32_e32 v80, v80, v128
	v_mul_f32_e32 v64, v64, v128
	v_mul_f32_e32 v197, v147, v64
	v_fma_f32 v197, v146, v80, -v197
	v_mul_f32_e32 v142, v146, v64
	v_fmac_f32_e32 v142, v147, v80
	v_cvt_pk_bf16_f32 v143, v197, v142
	ds_write_b16 v144, v143 offset:8192
	ds_write_b16_d16_hi v144, v143 offset:8256
	v_mul_f32_e32 v139, v197, v197
	v_fmac_f32_e32 v139, v142, v142
	v_max_f32_e32 v251, v251, v139
	v_mul_f32_e32 v113, v113, v129
	v_mul_f32_e32 v97, v97, v129
	v_mul_f32_e32 v136, v149, v97
	v_fma_f32 v136, v148, v113, -v136
	v_mul_f32_e32 v137, v148, v97
	v_fmac_f32_e32 v137, v149, v113
	v_cvt_pk_bf16_f32 v141, v136, v137
	ds_write_b16 v144, v141 offset:128
	ds_write_b16_d16_hi v144, v141 offset:192
	v_mul_f32_e32 v140, v136, v136
	v_fmac_f32_e32 v140, v137, v137
	v_max_f32_e32 v250, v250, v140
	v_mul_f32_e32 v81, v81, v129
	v_mul_f32_e32 v65, v65, v129
	v_mul_f32_e32 v197, v149, v65
	v_fma_f32 v197, v148, v81, -v197
	v_mul_f32_e32 v142, v148, v65
	v_fmac_f32_e32 v142, v149, v81
	v_cvt_pk_bf16_f32 v143, v197, v142
	ds_write_b16 v144, v143 offset:8320
	ds_write_b16_d16_hi v144, v143 offset:8384
	v_mul_f32_e32 v139, v197, v197
	v_fmac_f32_e32 v139, v142, v142
	v_max_f32_e32 v251, v251, v139
	v_mul_f32_e32 v114, v114, v130
	v_mul_f32_e32 v98, v98, v130
	v_mul_f32_e32 v136, v151, v98
	v_fma_f32 v136, v150, v114, -v136
	v_mul_f32_e32 v137, v150, v98
	v_fmac_f32_e32 v137, v151, v114
	v_cvt_pk_bf16_f32 v141, v136, v137
	ds_write_b16 v144, v141 offset:256
	ds_write_b16_d16_hi v144, v141 offset:320
	v_mul_f32_e32 v140, v136, v136
	v_fmac_f32_e32 v140, v137, v137
	v_max_f32_e32 v250, v250, v140
	v_mul_f32_e32 v82, v82, v130
	v_mul_f32_e32 v66, v66, v130
	v_mul_f32_e32 v197, v151, v66
	v_fma_f32 v197, v150, v82, -v197
	v_mul_f32_e32 v142, v150, v66
	v_fmac_f32_e32 v142, v151, v82
	v_cvt_pk_bf16_f32 v143, v197, v142
	ds_write_b16 v144, v143 offset:8448
	ds_write_b16_d16_hi v144, v143 offset:8512
	v_mul_f32_e32 v139, v197, v197
	v_fmac_f32_e32 v139, v142, v142
	v_max_f32_e32 v251, v251, v139
	v_mul_f32_e32 v115, v115, v131
	v_mul_f32_e32 v99, v99, v131
	v_mul_f32_e32 v136, v153, v99
	v_fma_f32 v136, v152, v115, -v136
	v_mul_f32_e32 v137, v152, v99
	v_fmac_f32_e32 v137, v153, v115
	v_cvt_pk_bf16_f32 v141, v136, v137
	ds_write_b16 v144, v141 offset:384
	ds_write_b16_d16_hi v144, v141 offset:448
	v_mul_f32_e32 v140, v136, v136
	v_fmac_f32_e32 v140, v137, v137
	v_max_f32_e32 v250, v250, v140
	v_mul_f32_e32 v83, v83, v131
	v_mul_f32_e32 v67, v67, v131
	v_mul_f32_e32 v197, v153, v67
	v_fma_f32 v197, v152, v83, -v197
	v_mul_f32_e32 v142, v152, v67
	v_fmac_f32_e32 v142, v153, v83
	v_cvt_pk_bf16_f32 v143, v197, v142
	ds_write_b16 v144, v143 offset:8576
	ds_write_b16_d16_hi v144, v143 offset:8640
	v_mul_f32_e32 v139, v197, v197
	v_fmac_f32_e32 v139, v142, v142
	v_max_f32_e32 v251, v251, v139
	ds_read_b128 v[128:131], v196 offset:32
	s_waitcnt lgkmcnt(0)
	v_mul_f32_e32 v128, v135, v128
	v_mul_f32_e32 v129, v135, v129
	v_mul_f32_e32 v130, v135, v130
	v_mul_f32_e32 v131, v135, v131
	v_mul_f32_e32 v116, v116, v128
	v_mul_f32_e32 v100, v100, v128
	v_mul_f32_e32 v136, v155, v100
	v_fma_f32 v136, v154, v116, -v136
	v_mul_f32_e32 v137, v154, v100
	v_fmac_f32_e32 v137, v155, v116
	v_cvt_pk_bf16_f32 v141, v136, v137
	ds_write_b16 v144, v141 offset:1024
	ds_write_b16_d16_hi v144, v141 offset:1088
	v_mul_f32_e32 v140, v136, v136
	v_fmac_f32_e32 v140, v137, v137
	v_max_f32_e32 v250, v250, v140
	v_mul_f32_e32 v84, v84, v128
	v_mul_f32_e32 v68, v68, v128
	v_mul_f32_e32 v197, v155, v68
	v_fma_f32 v197, v154, v84, -v197
	v_mul_f32_e32 v142, v154, v68
	v_fmac_f32_e32 v142, v155, v84
	v_cvt_pk_bf16_f32 v143, v197, v142
	ds_write_b16 v144, v143 offset:9216
	ds_write_b16_d16_hi v144, v143 offset:9280
	v_mul_f32_e32 v139, v197, v197
	v_fmac_f32_e32 v139, v142, v142
	v_max_f32_e32 v251, v251, v139
	v_mul_f32_e32 v117, v117, v129
	v_mul_f32_e32 v101, v101, v129
	v_mul_f32_e32 v136, v157, v101
	v_fma_f32 v136, v156, v117, -v136
	v_mul_f32_e32 v137, v156, v101
	v_fmac_f32_e32 v137, v157, v117
	v_cvt_pk_bf16_f32 v141, v136, v137
	ds_write_b16 v144, v141 offset:1152
	ds_write_b16_d16_hi v144, v141 offset:1216
	v_mul_f32_e32 v140, v136, v136
	v_fmac_f32_e32 v140, v137, v137
	v_max_f32_e32 v250, v250, v140
	v_mul_f32_e32 v85, v85, v129
	v_mul_f32_e32 v69, v69, v129
	v_mul_f32_e32 v197, v157, v69
	v_fma_f32 v197, v156, v85, -v197
	v_mul_f32_e32 v142, v156, v69
	v_fmac_f32_e32 v142, v157, v85
	v_cvt_pk_bf16_f32 v143, v197, v142
	ds_write_b16 v144, v143 offset:9344
	ds_write_b16_d16_hi v144, v143 offset:9408
	v_mul_f32_e32 v139, v197, v197
	v_fmac_f32_e32 v139, v142, v142
	v_max_f32_e32 v251, v251, v139
	v_mul_f32_e32 v118, v118, v130
	v_mul_f32_e32 v102, v102, v130
	v_mul_f32_e32 v136, v159, v102
	v_fma_f32 v136, v158, v118, -v136
	v_mul_f32_e32 v137, v158, v102
	v_fmac_f32_e32 v137, v159, v118
	v_cvt_pk_bf16_f32 v141, v136, v137
	ds_write_b16 v144, v141 offset:1280
	ds_write_b16_d16_hi v144, v141 offset:1344
	v_mul_f32_e32 v140, v136, v136
	v_fmac_f32_e32 v140, v137, v137
	v_max_f32_e32 v250, v250, v140
	v_mul_f32_e32 v86, v86, v130
	v_mul_f32_e32 v70, v70, v130
	v_mul_f32_e32 v197, v159, v70
	v_fma_f32 v197, v158, v86, -v197
	v_mul_f32_e32 v142, v158, v70
	v_fmac_f32_e32 v142, v159, v86
	v_cvt_pk_bf16_f32 v143, v197, v142
	ds_write_b16 v144, v143 offset:9472
	ds_write_b16_d16_hi v144, v143 offset:9536
	v_mul_f32_e32 v139, v197, v197
	v_fmac_f32_e32 v139, v142, v142
	v_max_f32_e32 v251, v251, v139
	v_mul_f32_e32 v119, v119, v131
	v_mul_f32_e32 v103, v103, v131
	v_mul_f32_e32 v136, v161, v103
	v_fma_f32 v136, v160, v119, -v136
	v_mul_f32_e32 v137, v160, v103
	v_fmac_f32_e32 v137, v161, v119
	v_cvt_pk_bf16_f32 v141, v136, v137
	ds_write_b16 v144, v141 offset:1408
	ds_write_b16_d16_hi v144, v141 offset:1472
	v_mul_f32_e32 v140, v136, v136
	v_fmac_f32_e32 v140, v137, v137
	v_max_f32_e32 v250, v250, v140
	v_mul_f32_e32 v87, v87, v131
	v_mul_f32_e32 v71, v71, v131
	v_mul_f32_e32 v197, v161, v71
	v_fma_f32 v197, v160, v87, -v197
	v_mul_f32_e32 v142, v160, v71
	v_fmac_f32_e32 v142, v161, v87
	v_cvt_pk_bf16_f32 v143, v197, v142
	ds_write_b16 v144, v143 offset:9600
	ds_write_b16_d16_hi v144, v143 offset:9664
	v_mul_f32_e32 v139, v197, v197
	v_fmac_f32_e32 v139, v142, v142
	v_max_f32_e32 v251, v251, v139
	ds_read_b128 v[128:131], v196 offset:64
	s_waitcnt lgkmcnt(0)
; DI u16 f2bf(float a) { return (u16)(pack2(a, 0.f) & 0xffffu); }
; DI int crow(int reg, int g) { return (reg & 3) + 8 * (reg >> 2) + 4 * g; }
; template <bool TR>
; DI void gemm_in_tile(const P& p, int l, int id, char* smem) {
;     ...
;         const int rl = 64 * wr + 32 * rb + crow(reg, g);
;         const int tok = m0 + rl;
;         const float rs = rs_s[rl] * qs;
;         const int pos = tok & 8191, b = tok >> 13;
;         const float2 cs = p.rope[pos * 32 + li];
; #pragma unroll
;         for (int c = 0; c < 2; ++c) {
;           const float x1 = acc[rb][2 * c][reg] * rs, x2 = acc[rb][2 * c + 1][reg] * rs;
;           const float o1 = x1 * cs.x - x2 * cs.y, o2 = x2 * cs.x + x1 * cs.y;
;           const size_t base = ((size_t)(((b * 4 + h) * 2 + c) * SEQ + pos)) * 64;
;           dst[base + li] = f2bf(o1);
;           dst[base + 32 + li] = f2bf(o2);
;           if (c == 0) kl0 = fmaxf(kl0, o1 * o1 + o2 * o2); else kl1 = fmaxf(kl1, o1 * o1 + o2 * o2);
	v_mul_f32_e32 v128, v135, v128
	v_mul_f32_e32 v129, v135, v129
	v_mul_f32_e32 v130, v135, v130
	v_mul_f32_e32 v131, v135, v131
	v_mul_f32_e32 v120, v120, v128
	v_mul_f32_e32 v104, v104, v128
	v_mul_f32_e32 v136, v163, v104
	v_fma_f32 v136, v162, v120, -v136
	v_mul_f32_e32 v137, v162, v104
	v_fmac_f32_e32 v137, v163, v120
	v_cvt_pk_bf16_f32 v141, v136, v137
	ds_write_b16 v144, v141 offset:2048
	ds_write_b16_d16_hi v144, v141 offset:2112
	v_mul_f32_e32 v140, v136, v136
	v_fmac_f32_e32 v140, v137, v137
	v_max_f32_e32 v250, v250, v140
	v_mul_f32_e32 v88, v88, v128
	v_mul_f32_e32 v72, v72, v128
	v_mul_f32_e32 v197, v163, v72
	v_fma_f32 v197, v162, v88, -v197
	v_mul_f32_e32 v142, v162, v72
	v_fmac_f32_e32 v142, v163, v88
	v_cvt_pk_bf16_f32 v143, v197, v142
	ds_write_b16 v144, v143 offset:10240
	ds_write_b16_d16_hi v144, v143 offset:10304
	v_mul_f32_e32 v139, v197, v197
	v_fmac_f32_e32 v139, v142, v142
	v_max_f32_e32 v251, v251, v139
	v_mul_f32_e32 v121, v121, v129
	v_mul_f32_e32 v105, v105, v129
	v_mul_f32_e32 v136, v165, v105
	v_fma_f32 v136, v164, v121, -v136
	v_mul_f32_e32 v137, v164, v105
	v_fmac_f32_e32 v137, v165, v121
	v_cvt_pk_bf16_f32 v141, v136, v137
	ds_write_b16 v144, v141 offset:2176
	ds_write_b16_d16_hi v144, v141 offset:2240
	v_mul_f32_e32 v140, v136, v136
	v_fmac_f32_e32 v140, v137, v137
	v_max_f32_e32 v250, v250, v140
	v_mul_f32_e32 v89, v89, v129
	v_mul_f32_e32 v73, v73, v129
	v_mul_f32_e32 v197, v165, v73
	v_fma_f32 v197, v164, v89, -v197
	v_mul_f32_e32 v142, v164, v73
	v_fmac_f32_e32 v142, v165, v89
	v_cvt_pk_bf16_f32 v143, v197, v142
	ds_write_b16 v144, v143 offset:10368
	ds_write_b16_d16_hi v144, v143 offset:10432
	v_mul_f32_e32 v139, v197, v197
	v_fmac_f32_e32 v139, v142, v142
	v_max_f32_e32 v251, v251, v139
	v_mul_f32_e32 v122, v122, v130
	v_mul_f32_e32 v106, v106, v130
	v_mul_f32_e32 v136, v167, v106
	v_fma_f32 v136, v166, v122, -v136
	v_mul_f32_e32 v137, v166, v106
	v_fmac_f32_e32 v137, v167, v122
	v_cvt_pk_bf16_f32 v141, v136, v137
	ds_write_b16 v144, v141 offset:2304
	ds_write_b16_d16_hi v144, v141 offset:2368
	v_mul_f32_e32 v140, v136, v136
	v_fmac_f32_e32 v140, v137, v137
	v_max_f32_e32 v250, v250, v140
	v_mul_f32_e32 v90, v90, v130
	v_mul_f32_e32 v74, v74, v130
	v_mul_f32_e32 v197, v167, v74
	v_fma_f32 v197, v166, v90, -v197
	v_mul_f32_e32 v142, v166, v74
	v_fmac_f32_e32 v142, v167, v90
	v_cvt_pk_bf16_f32 v143, v197, v142
	ds_write_b16 v144, v143 offset:10496
	ds_write_b16_d16_hi v144, v143 offset:10560
	v_mul_f32_e32 v139, v197, v197
	v_fmac_f32_e32 v139, v142, v142
	v_max_f32_e32 v251, v251, v139
	v_mul_f32_e32 v123, v123, v131
	v_mul_f32_e32 v107, v107, v131
	v_mul_f32_e32 v136, v169, v107
	v_fma_f32 v136, v168, v123, -v136
	v_mul_f32_e32 v137, v168, v107
	v_fmac_f32_e32 v137, v169, v123
	v_cvt_pk_bf16_f32 v141, v136, v137
	ds_write_b16 v144, v141 offset:2432
	ds_write_b16_d16_hi v144, v141 offset:2496
	v_mul_f32_e32 v140, v136, v136
	v_fmac_f32_e32 v140, v137, v137
	v_max_f32_e32 v250, v250, v140
	v_mul_f32_e32 v91, v91, v131
	v_mul_f32_e32 v75, v75, v131
	v_mul_f32_e32 v197, v169, v75
	v_fma_f32 v197, v168, v91, -v197
	v_mul_f32_e32 v142, v168, v75
	v_fmac_f32_e32 v142, v169, v91
	v_cvt_pk_bf16_f32 v143, v197, v142
	ds_write_b16 v144, v143 offset:10624
	ds_write_b16_d16_hi v144, v143 offset:10688
	v_mul_f32_e32 v139, v197, v197
	v_fmac_f32_e32 v139, v142, v142
	v_max_f32_e32 v251, v251, v139
	ds_read_b128 v[128:131], v196 offset:96
	s_waitcnt lgkmcnt(0)
	v_mul_f32_e32 v128, v135, v128
	v_mul_f32_e32 v129, v135, v129
	v_mul_f32_e32 v130, v135, v130
	v_mul_f32_e32 v131, v135, v131
	v_mul_f32_e32 v124, v124, v128
	v_mul_f32_e32 v108, v108, v128
	v_mul_f32_e32 v136, v171, v108
	v_fma_f32 v136, v170, v124, -v136
	v_mul_f32_e32 v137, v170, v108
	v_fmac_f32_e32 v137, v171, v124
	v_cvt_pk_bf16_f32 v141, v136, v137
	ds_write_b16 v144, v141 offset:3072
	ds_write_b16_d16_hi v144, v141 offset:3136
	v_mul_f32_e32 v140, v136, v136
	v_fmac_f32_e32 v140, v137, v137
	v_max_f32_e32 v250, v250, v140
	v_mul_f32_e32 v92, v92, v128
	v_mul_f32_e32 v76, v76, v128
	v_mul_f32_e32 v197, v171, v76
	v_fma_f32 v197, v170, v92, -v197
	v_mul_f32_e32 v142, v170, v76
	v_fmac_f32_e32 v142, v171, v92
	v_cvt_pk_bf16_f32 v143, v197, v142
	ds_write_b16 v144, v143 offset:11264
	ds_write_b16_d16_hi v144, v143 offset:11328
	v_mul_f32_e32 v139, v197, v197
	v_fmac_f32_e32 v139, v142, v142
	v_max_f32_e32 v251, v251, v139
	v_mul_f32_e32 v125, v125, v129
	v_mul_f32_e32 v109, v109, v129
	v_mul_f32_e32 v136, v173, v109
	v_fma_f32 v136, v172, v125, -v136
	v_mul_f32_e32 v137, v172, v109
	v_fmac_f32_e32 v137, v173, v125
	v_cvt_pk_bf16_f32 v141, v136, v137
	ds_write_b16 v144, v141 offset:3200
	ds_write_b16_d16_hi v144, v141 offset:3264
	v_mul_f32_e32 v140, v136, v136
	v_fmac_f32_e32 v140, v137, v137
	v_max_f32_e32 v250, v250, v140
	v_mul_f32_e32 v93, v93, v129
	v_mul_f32_e32 v77, v77, v129
	v_mul_f32_e32 v197, v173, v77
	v_fma_f32 v197, v172, v93, -v197
	v_mul_f32_e32 v142, v172, v77
	v_fmac_f32_e32 v142, v173, v93
	v_cvt_pk_bf16_f32 v143, v197, v142
	ds_write_b16 v144, v143 offset:11392
	ds_write_b16_d16_hi v144, v143 offset:11456
	v_mul_f32_e32 v139, v197, v197
	v_fmac_f32_e32 v139, v142, v142
	v_max_f32_e32 v251, v251, v139
	v_mul_f32_e32 v126, v126, v130
	v_mul_f32_e32 v110, v110, v130
	v_mul_f32_e32 v136, v175, v110
	v_fma_f32 v136, v174, v126, -v136
	v_mul_f32_e32 v137, v174, v110
	v_fmac_f32_e32 v137, v175, v126
	v_cvt_pk_bf16_f32 v141, v136, v137
	ds_write_b16 v144, v141 offset:3328
	ds_write_b16_d16_hi v144, v141 offset:3392
	v_mul_f32_e32 v140, v136, v136
	v_fmac_f32_e32 v140, v137, v137
	v_max_f32_e32 v250, v250, v140
	v_mul_f32_e32 v94, v94, v130
	v_mul_f32_e32 v78, v78, v130
	v_mul_f32_e32 v197, v175, v78
	v_fma_f32 v197, v174, v94, -v197
	v_mul_f32_e32 v142, v174, v78
	v_fmac_f32_e32 v142, v175, v94
	v_cvt_pk_bf16_f32 v143, v197, v142
	ds_write_b16 v144, v143 offset:11520
	ds_write_b16_d16_hi v144, v143 offset:11584
	v_mul_f32_e32 v139, v197, v197
	v_fmac_f32_e32 v139, v142, v142
	v_max_f32_e32 v251, v251, v139
	v_mul_f32_e32 v127, v127, v131
	v_mul_f32_e32 v111, v111, v131
	v_mul_f32_e32 v136, v221, v111
	v_fma_f32 v136, v220, v127, -v136
	v_mul_f32_e32 v137, v220, v111
	v_fmac_f32_e32 v137, v221, v127
	v_cvt_pk_bf16_f32 v141, v136, v137
	ds_write_b16 v144, v141 offset:3456
	ds_write_b16_d16_hi v144, v141 offset:3520
	v_mul_f32_e32 v140, v136, v136
	v_fmac_f32_e32 v140, v137, v137
	v_max_f32_e32 v250, v250, v140
	v_mul_f32_e32 v95, v95, v131
	v_mul_f32_e32 v79, v79, v131
	v_mul_f32_e32 v197, v221, v79
	v_fma_f32 v197, v220, v95, -v197
	v_mul_f32_e32 v142, v220, v79
	v_fmac_f32_e32 v142, v221, v95
	v_cvt_pk_bf16_f32 v143, v197, v142
	ds_write_b16 v144, v143 offset:11648
	ds_write_b16_d16_hi v144, v143 offset:11712
	v_mul_f32_e32 v139, v197, v197
	v_fmac_f32_e32 v139, v142, v142
	v_max_f32_e32 v251, v251, v139
	ds_read_b128 v[128:131], v196 offset:128
	s_waitcnt lgkmcnt(0)
; DI u16 f2bf(float a) { return (u16)(pack2(a, 0.f) & 0xffffu); }
; DI int crow(int reg, int g) { return (reg & 3) + 8 * (reg >> 2) + 4 * g; }
; template <bool TR>
; DI void gemm_in_tile(const P& p, int l, int id, char* smem) {
;     ...
;         const int rl = 64 * wr + 32 * rb + crow(reg, g);
;         const int tok = m0 + rl;
;         const float rs = rs_s[rl] * qs;
;         const int pos = tok & 8191, b = tok >> 13;
;         const float2 cs = p.rope[pos * 32 + li];
; #pragma unroll
;         for (int c = 0; c < 2; ++c) {
;           const float x1 = acc[rb][2 * c][reg] * rs, x2 = acc[rb][2 * c + 1][reg] * rs;
;           const float o1 = x1 * cs.x - x2 * cs.y, o2 = x2 * cs.x + x1 * cs.y;
;           const size_t base = ((size_t)(((b * 4 + h) * 2 + c) * SEQ + pos)) * 64;
;           dst[base + li] = f2bf(o1);
;           dst[base + 32 + li] = f2bf(o2);
;           if (c == 0) kl0 = fmaxf(kl0, o1 * o1 + o2 * o2); else kl1 = fmaxf(kl1, o1 * o1 + o2 * o2);
	v_mul_f32_e32 v128, v135, v128
	v_mul_f32_e32 v129, v135, v129
	v_mul_f32_e32 v130, v135, v130
	v_mul_f32_e32 v131, v135, v131
	v_mul_f32_e32 v48, v48, v128
	v_mul_f32_e32 v32, v32, v128
	v_mul_f32_e32 v136, v223, v32
	v_fma_f32 v136, v222, v48, -v136
	v_mul_f32_e32 v137, v222, v32
	v_fmac_f32_e32 v137, v223, v48
	v_cvt_pk_bf16_f32 v141, v136, v137
	ds_write_b16 v144, v141 offset:4096
	ds_write_b16_d16_hi v144, v141 offset:4160
	v_mul_f32_e32 v140, v136, v136
	v_fmac_f32_e32 v140, v137, v137
	v_max_f32_e32 v250, v250, v140
	v_mul_f32_e32 v16, v16, v128
	v_mul_f32_e32 v0, v0, v128
	v_mul_f32_e32 v197, v223, v0
	v_fma_f32 v197, v222, v16, -v197
	v_mul_f32_e32 v142, v222, v0
	v_fmac_f32_e32 v142, v223, v16
	v_cvt_pk_bf16_f32 v143, v197, v142
	ds_write_b16 v144, v143 offset:12288
	ds_write_b16_d16_hi v144, v143 offset:12352
	v_mul_f32_e32 v139, v197, v197
	v_fmac_f32_e32 v139, v142, v142
	v_max_f32_e32 v251, v251, v139
	v_mul_f32_e32 v49, v49, v129
	v_mul_f32_e32 v33, v33, v129
	v_mul_f32_e32 v136, v225, v33
	v_fma_f32 v136, v224, v49, -v136
	v_mul_f32_e32 v137, v224, v33
	v_fmac_f32_e32 v137, v225, v49
	v_cvt_pk_bf16_f32 v141, v136, v137
	ds_write_b16 v144, v141 offset:4224
	ds_write_b16_d16_hi v144, v141 offset:4288
	v_mul_f32_e32 v140, v136, v136
	v_fmac_f32_e32 v140, v137, v137
	v_max_f32_e32 v250, v250, v140
	v_mul_f32_e32 v17, v17, v129
	v_mul_f32_e32 v1, v1, v129
	v_mul_f32_e32 v197, v225, v1
	v_fma_f32 v197, v224, v17, -v197
	v_mul_f32_e32 v142, v224, v1
	v_fmac_f32_e32 v142, v225, v17
	v_cvt_pk_bf16_f32 v143, v197, v142
	ds_write_b16 v144, v143 offset:12416
	ds_write_b16_d16_hi v144, v143 offset:12480
	v_mul_f32_e32 v139, v197, v197
	v_fmac_f32_e32 v139, v142, v142
	v_max_f32_e32 v251, v251, v139
	v_mul_f32_e32 v50, v50, v130
	v_mul_f32_e32 v34, v34, v130
	v_mul_f32_e32 v136, v227, v34
	v_fma_f32 v136, v226, v50, -v136
	v_mul_f32_e32 v137, v226, v34
	v_fmac_f32_e32 v137, v227, v50
	v_cvt_pk_bf16_f32 v141, v136, v137
	ds_write_b16 v144, v141 offset:4352
	ds_write_b16_d16_hi v144, v141 offset:4416
	v_mul_f32_e32 v140, v136, v136
	v_fmac_f32_e32 v140, v137, v137
	v_max_f32_e32 v250, v250, v140
	v_mul_f32_e32 v18, v18, v130
	v_mul_f32_e32 v2, v2, v130
	v_mul_f32_e32 v197, v227, v2
	v_fma_f32 v197, v226, v18, -v197
	v_mul_f32_e32 v142, v226, v2
	v_fmac_f32_e32 v142, v227, v18
	v_cvt_pk_bf16_f32 v143, v197, v142
	ds_write_b16 v144, v143 offset:12544
	ds_write_b16_d16_hi v144, v143 offset:12608
	v_mul_f32_e32 v139, v197, v197
	v_fmac_f32_e32 v139, v142, v142
	v_max_f32_e32 v251, v251, v139
	v_mul_f32_e32 v51, v51, v131
	v_mul_f32_e32 v35, v35, v131
	v_mul_f32_e32 v136, v229, v35
	v_fma_f32 v136, v228, v51, -v136
	v_mul_f32_e32 v137, v228, v35
	v_fmac_f32_e32 v137, v229, v51
	v_cvt_pk_bf16_f32 v141, v136, v137
	ds_write_b16 v144, v141 offset:4480
	ds_write_b16_d16_hi v144, v141 offset:4544
	v_mul_f32_e32 v140, v136, v136
	v_fmac_f32_e32 v140, v137, v137
	v_max_f32_e32 v250, v250, v140
	v_mul_f32_e32 v19, v19, v131
	v_mul_f32_e32 v3, v3, v131
	v_mul_f32_e32 v197, v229, v3
	v_fma_f32 v197, v228, v19, -v197
	v_mul_f32_e32 v142, v228, v3
	v_fmac_f32_e32 v142, v229, v19
	v_cvt_pk_bf16_f32 v143, v197, v142
	ds_write_b16 v144, v143 offset:12672
	ds_write_b16_d16_hi v144, v143 offset:12736
	v_mul_f32_e32 v139, v197, v197
	v_fmac_f32_e32 v139, v142, v142
	v_max_f32_e32 v251, v251, v139
	ds_read_b128 v[128:131], v196 offset:160
	s_waitcnt lgkmcnt(0)
	v_mul_f32_e32 v128, v135, v128
	v_mul_f32_e32 v129, v135, v129
	v_mul_f32_e32 v130, v135, v130
	v_mul_f32_e32 v131, v135, v131
	v_mul_f32_e32 v52, v52, v128
	v_mul_f32_e32 v36, v36, v128
	v_mul_f32_e32 v136, v231, v36
	v_fma_f32 v136, v230, v52, -v136
	v_mul_f32_e32 v137, v230, v36
	v_fmac_f32_e32 v137, v231, v52
	v_cvt_pk_bf16_f32 v141, v136, v137
	ds_write_b16 v144, v141 offset:5120
	ds_write_b16_d16_hi v144, v141 offset:5184
	v_mul_f32_e32 v140, v136, v136
	v_fmac_f32_e32 v140, v137, v137
	v_max_f32_e32 v250, v250, v140
	v_mul_f32_e32 v20, v20, v128
	v_mul_f32_e32 v4, v4, v128
	v_mul_f32_e32 v197, v231, v4
	v_fma_f32 v197, v230, v20, -v197
	v_mul_f32_e32 v142, v230, v4
	v_fmac_f32_e32 v142, v231, v20
	v_cvt_pk_bf16_f32 v143, v197, v142
	ds_write_b16 v144, v143 offset:13312
	ds_write_b16_d16_hi v144, v143 offset:13376
	v_mul_f32_e32 v139, v197, v197
	v_fmac_f32_e32 v139, v142, v142
	v_max_f32_e32 v251, v251, v139
	v_mul_f32_e32 v53, v53, v129
	v_mul_f32_e32 v37, v37, v129
	v_mul_f32_e32 v136, v233, v37
	v_fma_f32 v136, v232, v53, -v136
	v_mul_f32_e32 v137, v232, v37
	v_fmac_f32_e32 v137, v233, v53
	v_cvt_pk_bf16_f32 v141, v136, v137
	ds_write_b16 v144, v141 offset:5248
	ds_write_b16_d16_hi v144, v141 offset:5312
	v_mul_f32_e32 v140, v136, v136
	v_fmac_f32_e32 v140, v137, v137
	v_max_f32_e32 v250, v250, v140
	v_mul_f32_e32 v21, v21, v129
	v_mul_f32_e32 v5, v5, v129
	v_mul_f32_e32 v197, v233, v5
	v_fma_f32 v197, v232, v21, -v197
	v_mul_f32_e32 v142, v232, v5
	v_fmac_f32_e32 v142, v233, v21
	v_cvt_pk_bf16_f32 v143, v197, v142
	ds_write_b16 v144, v143 offset:13440
	ds_write_b16_d16_hi v144, v143 offset:13504
	v_mul_f32_e32 v139, v197, v197
	v_fmac_f32_e32 v139, v142, v142
	v_max_f32_e32 v251, v251, v139
	v_mul_f32_e32 v54, v54, v130
	v_mul_f32_e32 v38, v38, v130
	v_mul_f32_e32 v136, v235, v38
	v_fma_f32 v136, v234, v54, -v136
	v_mul_f32_e32 v137, v234, v38
	v_fmac_f32_e32 v137, v235, v54
	v_cvt_pk_bf16_f32 v141, v136, v137
	ds_write_b16 v144, v141 offset:5376
	ds_write_b16_d16_hi v144, v141 offset:5440
	v_mul_f32_e32 v140, v136, v136
	v_fmac_f32_e32 v140, v137, v137
	v_max_f32_e32 v250, v250, v140
	v_mul_f32_e32 v22, v22, v130
	v_mul_f32_e32 v6, v6, v130
	v_mul_f32_e32 v197, v235, v6
	v_fma_f32 v197, v234, v22, -v197
	v_mul_f32_e32 v142, v234, v6
	v_fmac_f32_e32 v142, v235, v22
	v_cvt_pk_bf16_f32 v143, v197, v142
	ds_write_b16 v144, v143 offset:13568
	ds_write_b16_d16_hi v144, v143 offset:13632
	v_mul_f32_e32 v139, v197, v197
	v_fmac_f32_e32 v139, v142, v142
	v_max_f32_e32 v251, v251, v139
	v_mul_f32_e32 v55, v55, v131
	v_mul_f32_e32 v39, v39, v131
	v_mul_f32_e32 v136, v237, v39
	v_fma_f32 v136, v236, v55, -v136
	v_mul_f32_e32 v137, v236, v39
	v_fmac_f32_e32 v137, v237, v55
	v_cvt_pk_bf16_f32 v141, v136, v137
	ds_write_b16 v144, v141 offset:5504
	ds_write_b16_d16_hi v144, v141 offset:5568
	v_mul_f32_e32 v140, v136, v136
	v_fmac_f32_e32 v140, v137, v137
	v_max_f32_e32 v250, v250, v140
	v_mul_f32_e32 v23, v23, v131
	v_mul_f32_e32 v7, v7, v131
	v_mul_f32_e32 v197, v237, v7
	v_fma_f32 v197, v236, v23, -v197
	v_mul_f32_e32 v142, v236, v7
	v_fmac_f32_e32 v142, v237, v23
	v_cvt_pk_bf16_f32 v143, v197, v142
	ds_write_b16 v144, v143 offset:13696
	ds_write_b16_d16_hi v144, v143 offset:13760
	v_mul_f32_e32 v139, v197, v197
	v_fmac_f32_e32 v139, v142, v142
	v_max_f32_e32 v251, v251, v139
	ds_read_b128 v[128:131], v196 offset:192
	s_waitcnt lgkmcnt(0)
; DI u16 f2bf(float a) { return (u16)(pack2(a, 0.f) & 0xffffu); }
; DI int crow(int reg, int g) { return (reg & 3) + 8 * (reg >> 2) + 4 * g; }
; template <bool TR>
; DI void gemm_in_tile(const P& p, int l, int id, char* smem) {
;     ...
;         const int rl = 64 * wr + 32 * rb + crow(reg, g);
;         const int tok = m0 + rl;
;         const float rs = rs_s[rl] * qs;
;         const int pos = tok & 8191, b = tok >> 13;
;         const float2 cs = p.rope[pos * 32 + li];
; #pragma unroll
;         for (int c = 0; c < 2; ++c) {
;           const float x1 = acc[rb][2 * c][reg] * rs, x2 = acc[rb][2 * c + 1][reg] * rs;
;           const float o1 = x1 * cs.x - x2 * cs.y, o2 = x2 * cs.x + x1 * cs.y;
;           const size_t base = ((size_t)(((b * 4 + h) * 2 + c) * SEQ + pos)) * 64;
;           dst[base + li] = f2bf(o1);
;           dst[base + 32 + li] = f2bf(o2);
;           if (c == 0) kl0 = fmaxf(kl0, o1 * o1 + o2 * o2); else kl1 = fmaxf(kl1, o1 * o1 + o2 * o2);
	v_mul_f32_e32 v128, v135, v128
	v_mul_f32_e32 v129, v135, v129
	v_mul_f32_e32 v130, v135, v130
	v_mul_f32_e32 v131, v135, v131
	v_mul_f32_e32 v56, v56, v128
	v_mul_f32_e32 v40, v40, v128
	v_mul_f32_e32 v136, v239, v40
	v_fma_f32 v136, v238, v56, -v136
	v_mul_f32_e32 v137, v238, v40
	v_fmac_f32_e32 v137, v239, v56
	v_cvt_pk_bf16_f32 v141, v136, v137
	ds_write_b16 v144, v141 offset:6144
	ds_write_b16_d16_hi v144, v141 offset:6208
	v_mul_f32_e32 v140, v136, v136
	v_fmac_f32_e32 v140, v137, v137
	v_max_f32_e32 v250, v250, v140
	v_mul_f32_e32 v24, v24, v128
	v_mul_f32_e32 v8, v8, v128
	v_mul_f32_e32 v197, v239, v8
	v_fma_f32 v197, v238, v24, -v197
	v_mul_f32_e32 v142, v238, v8
	v_fmac_f32_e32 v142, v239, v24
	v_cvt_pk_bf16_f32 v143, v197, v142
	ds_write_b16 v144, v143 offset:14336
	ds_write_b16_d16_hi v144, v143 offset:14400
	v_mul_f32_e32 v139, v197, v197
	v_fmac_f32_e32 v139, v142, v142
	v_max_f32_e32 v251, v251, v139
	v_mul_f32_e32 v57, v57, v129
	v_mul_f32_e32 v41, v41, v129
	v_mul_f32_e32 v136, v241, v41
	v_fma_f32 v136, v240, v57, -v136
	v_mul_f32_e32 v137, v240, v41
	v_fmac_f32_e32 v137, v241, v57
	v_cvt_pk_bf16_f32 v141, v136, v137
	ds_write_b16 v144, v141 offset:6272
	ds_write_b16_d16_hi v144, v141 offset:6336
	v_mul_f32_e32 v140, v136, v136
	v_fmac_f32_e32 v140, v137, v137
	v_max_f32_e32 v250, v250, v140
	v_mul_f32_e32 v25, v25, v129
	v_mul_f32_e32 v9, v9, v129
	v_mul_f32_e32 v197, v241, v9
	v_fma_f32 v197, v240, v25, -v197
	v_mul_f32_e32 v142, v240, v9
	v_fmac_f32_e32 v142, v241, v25
	v_cvt_pk_bf16_f32 v143, v197, v142
	ds_write_b16 v144, v143 offset:14464
	ds_write_b16_d16_hi v144, v143 offset:14528
	v_mul_f32_e32 v139, v197, v197
	v_fmac_f32_e32 v139, v142, v142
	v_max_f32_e32 v251, v251, v139
	v_mul_f32_e32 v58, v58, v130
	v_mul_f32_e32 v42, v42, v130
	v_mul_f32_e32 v136, v243, v42
	v_fma_f32 v136, v242, v58, -v136
	v_mul_f32_e32 v137, v242, v42
	v_fmac_f32_e32 v137, v243, v58
	v_cvt_pk_bf16_f32 v141, v136, v137
	ds_write_b16 v144, v141 offset:6400
	ds_write_b16_d16_hi v144, v141 offset:6464
	v_mul_f32_e32 v140, v136, v136
	v_fmac_f32_e32 v140, v137, v137
	v_max_f32_e32 v250, v250, v140
	v_mul_f32_e32 v26, v26, v130
	v_mul_f32_e32 v10, v10, v130
	v_mul_f32_e32 v197, v243, v10
	v_fma_f32 v197, v242, v26, -v197
	v_mul_f32_e32 v142, v242, v10
	v_fmac_f32_e32 v142, v243, v26
	v_cvt_pk_bf16_f32 v143, v197, v142
	ds_write_b16 v144, v143 offset:14592
	ds_write_b16_d16_hi v144, v143 offset:14656
	v_mul_f32_e32 v139, v197, v197
	v_fmac_f32_e32 v139, v142, v142
	v_max_f32_e32 v251, v251, v139
	v_mul_f32_e32 v59, v59, v131
	v_mul_f32_e32 v43, v43, v131
	v_mul_f32_e32 v136, v245, v43
	v_fma_f32 v136, v244, v59, -v136
	v_mul_f32_e32 v137, v244, v43
	v_fmac_f32_e32 v137, v245, v59
	v_cvt_pk_bf16_f32 v141, v136, v137
	ds_write_b16 v144, v141 offset:6528
	ds_write_b16_d16_hi v144, v141 offset:6592
	v_mul_f32_e32 v140, v136, v136
	v_fmac_f32_e32 v140, v137, v137
	v_max_f32_e32 v250, v250, v140
	v_mul_f32_e32 v27, v27, v131
	v_mul_f32_e32 v11, v11, v131
	v_mul_f32_e32 v197, v245, v11
	v_fma_f32 v197, v244, v27, -v197
	v_mul_f32_e32 v142, v244, v11
	v_fmac_f32_e32 v142, v245, v27
	v_cvt_pk_bf16_f32 v143, v197, v142
	ds_write_b16 v144, v143 offset:14720
	ds_write_b16_d16_hi v144, v143 offset:14784
	v_mul_f32_e32 v139, v197, v197
	v_fmac_f32_e32 v139, v142, v142
	v_max_f32_e32 v251, v251, v139
	ds_read_b128 v[128:131], v196 offset:224
	s_waitcnt lgkmcnt(0)
	v_mul_f32_e32 v128, v135, v128
	v_mul_f32_e32 v129, v135, v129
	v_mul_f32_e32 v130, v135, v130
	v_mul_f32_e32 v131, v135, v131
	v_mul_f32_e32 v60, v60, v128
	v_mul_f32_e32 v44, v44, v128
	v_mul_f32_e32 v136, v247, v44
	v_fma_f32 v136, v246, v60, -v136
	v_mul_f32_e32 v137, v246, v44
	v_fmac_f32_e32 v137, v247, v60
	v_cvt_pk_bf16_f32 v141, v136, v137
	ds_write_b16 v144, v141 offset:7168
	ds_write_b16_d16_hi v144, v141 offset:7232
	v_mul_f32_e32 v140, v136, v136
	v_fmac_f32_e32 v140, v137, v137
	v_max_f32_e32 v250, v250, v140
	v_mul_f32_e32 v28, v28, v128
	v_mul_f32_e32 v12, v12, v128
	v_mul_f32_e32 v197, v247, v12
	v_fma_f32 v197, v246, v28, -v197
	v_mul_f32_e32 v142, v246, v12
	v_fmac_f32_e32 v142, v247, v28
	v_cvt_pk_bf16_f32 v143, v197, v142
	ds_write_b16 v144, v143 offset:15360
	ds_write_b16_d16_hi v144, v143 offset:15424
	v_mul_f32_e32 v139, v197, v197
	v_fmac_f32_e32 v139, v142, v142
	v_max_f32_e32 v251, v251, v139
	v_mul_f32_e32 v61, v61, v129
	v_mul_f32_e32 v45, v45, v129
	v_mul_f32_e32 v136, v191, v45
	v_fma_f32 v136, v190, v61, -v136
	v_mul_f32_e32 v137, v190, v45
	v_fmac_f32_e32 v137, v191, v61
	v_cvt_pk_bf16_f32 v141, v136, v137
	ds_write_b16 v144, v141 offset:7296
	ds_write_b16_d16_hi v144, v141 offset:7360
	v_mul_f32_e32 v140, v136, v136
	v_fmac_f32_e32 v140, v137, v137
	v_max_f32_e32 v250, v250, v140
	v_mul_f32_e32 v29, v29, v129
	v_mul_f32_e32 v13, v13, v129
	v_mul_f32_e32 v197, v191, v13
	v_fma_f32 v197, v190, v29, -v197
	v_mul_f32_e32 v142, v190, v13
	v_fmac_f32_e32 v142, v191, v29
	v_cvt_pk_bf16_f32 v143, v197, v142
	ds_write_b16 v144, v143 offset:15488
	ds_write_b16_d16_hi v144, v143 offset:15552
	v_mul_f32_e32 v139, v197, v197
	v_fmac_f32_e32 v139, v142, v142
	v_max_f32_e32 v251, v251, v139
	v_mul_f32_e32 v62, v62, v130
	v_mul_f32_e32 v46, v46, v130
	v_mul_f32_e32 v136, v193, v46
	v_fma_f32 v136, v192, v62, -v136
	v_mul_f32_e32 v137, v192, v46
	v_fmac_f32_e32 v137, v193, v62
	v_cvt_pk_bf16_f32 v141, v136, v137
	ds_write_b16 v144, v141 offset:7424
	ds_write_b16_d16_hi v144, v141 offset:7488
	v_mul_f32_e32 v140, v136, v136
	v_fmac_f32_e32 v140, v137, v137
	v_max_f32_e32 v250, v250, v140
	v_mul_f32_e32 v30, v30, v130
	v_mul_f32_e32 v14, v14, v130
	v_mul_f32_e32 v197, v193, v14
	v_fma_f32 v197, v192, v30, -v197
	v_mul_f32_e32 v142, v192, v14
	v_fmac_f32_e32 v142, v193, v30
	v_cvt_pk_bf16_f32 v143, v197, v142
	ds_write_b16 v144, v143 offset:15616
	ds_write_b16_d16_hi v144, v143 offset:15680
	v_mul_f32_e32 v139, v197, v197
	v_fmac_f32_e32 v139, v142, v142
	v_max_f32_e32 v251, v251, v139
	v_mul_f32_e32 v63, v63, v131
	v_mul_f32_e32 v47, v47, v131
	v_mul_f32_e32 v136, v195, v47
	v_fma_f32 v136, v194, v63, -v136
	v_mul_f32_e32 v137, v194, v47
	v_fmac_f32_e32 v137, v195, v63
	v_cvt_pk_bf16_f32 v141, v136, v137
	ds_write_b16 v144, v141 offset:7552
	ds_write_b16_d16_hi v144, v141 offset:7616
	v_mul_f32_e32 v140, v136, v136
	v_fmac_f32_e32 v140, v137, v137
	v_max_f32_e32 v250, v250, v140
	v_mul_f32_e32 v31, v31, v131
	v_mul_f32_e32 v15, v15, v131
	v_mul_f32_e32 v197, v195, v15
	v_fma_f32 v197, v194, v31, -v197
	v_mul_f32_e32 v142, v194, v15
	v_fmac_f32_e32 v142, v195, v31
	v_cvt_pk_bf16_f32 v143, v197, v142
	ds_write_b16 v144, v143 offset:15744
	ds_write_b16_d16_hi v144, v143 offset:15808
	v_mul_f32_e32 v139, v197, v197
	v_fmac_f32_e32 v139, v142, v142
	v_max_f32_e32 v251, v251, v139
	s_waitcnt lgkmcnt(0)
; DI u16 f2bf(float a) { return (u16)(pack2(a, 0.f) & 0xffffu); }
; template <bool TR>
; DI void gemm_in_tile(const P& p, int l, int id, char* smem) {
;     ...
;           dst[base + li] = f2bf(o1);
;           dst[base + 32 + li] = f2bf(o2);
;           if (c == 0) kl0 = fmaxf(kl0, o1 * o1 + o2 * o2); else kl1 = fmaxf(kl1, o1 * o1 + o2 * o2);
;         }
;       }
;     }
;     if (!isq) {
; #pragma unroll
;       for (int m = 16; m >= 1; m >>= 1) { kl0 += __shfl_xor(kl0, m); kl1 += __shfl_xor(kl1, m); }
;       kl0 = fmaxf(kl0, __shfl_xor(kl0, 32)) * 1.02f;
;       kl1 = fmaxf(kl1, __shfl_xor(kl1, 32)) * 1.02f;
;       if (lane == 0) {
;         atomicMax(p.kmax + (m0 >> 13) * 8 + h * 2 + 0, __float_as_uint(kl0));
;         atomicMax(p.kmax + (m0 >> 13) * 8 + h * 2 + 1, __float_as_uint(kl1));
;       }
	ds_read_b128 v[8:11], v145 offset:0
	ds_read_b128 v[12:15], v145 offset:1024
	ds_read_b128 v[16:19], v145 offset:2048
	ds_read_b128 v[20:23], v145 offset:3072
	ds_read_b128 v[24:27], v145 offset:4096
	ds_read_b128 v[28:31], v145 offset:5120
	ds_read_b128 v[32:35], v145 offset:6144
	ds_read_b128 v[36:39], v145 offset:7168
	ds_read_b128 v[40:43], v145 offset:8192
	ds_read_b128 v[44:47], v145 offset:9216
	ds_read_b128 v[48:51], v145 offset:10240
	ds_read_b128 v[52:55], v145 offset:11264
	ds_read_b128 v[56:59], v145 offset:12288
	ds_read_b128 v[60:63], v145 offset:13312
	ds_read_b128 v[64:67], v145 offset:14336
	ds_read_b128 v[68:71], v145 offset:15360
	s_waitcnt lgkmcnt(15)
	global_store_dwordx4 v249, v[8:11], s[98:99]
	v_add_u32_e32 v249, 0x400, v249
	s_waitcnt lgkmcnt(14)
	global_store_dwordx4 v249, v[12:15], s[98:99]
	v_add_u32_e32 v249, 0x400, v249
	s_waitcnt lgkmcnt(13)
	global_store_dwordx4 v249, v[16:19], s[98:99]
	v_add_u32_e32 v249, 0x400, v249
	s_waitcnt lgkmcnt(12)
	global_store_dwordx4 v249, v[20:23], s[98:99]
	v_add_u32_e32 v249, 0x400, v249
	s_waitcnt lgkmcnt(11)
	global_store_dwordx4 v249, v[24:27], s[98:99]
	v_add_u32_e32 v249, 0x400, v249
	s_waitcnt lgkmcnt(10)
	global_store_dwordx4 v249, v[28:31], s[98:99]
	v_add_u32_e32 v249, 0x400, v249
	s_waitcnt lgkmcnt(9)
	global_store_dwordx4 v249, v[32:35], s[98:99]
	v_add_u32_e32 v249, 0x400, v249
	s_waitcnt lgkmcnt(8)
	global_store_dwordx4 v249, v[36:39], s[98:99]
	v_add_u32_e32 v249, 0xfe400, v249
	s_waitcnt lgkmcnt(7)
	global_store_dwordx4 v249, v[40:43], s[98:99]
	v_add_u32_e32 v249, 0x400, v249
	s_waitcnt lgkmcnt(6)
	global_store_dwordx4 v249, v[44:47], s[98:99]
	v_add_u32_e32 v249, 0x400, v249
	s_waitcnt lgkmcnt(5)
	global_store_dwordx4 v249, v[48:51], s[98:99]
	v_add_u32_e32 v249, 0x400, v249
	s_waitcnt lgkmcnt(4)
	global_store_dwordx4 v249, v[52:55], s[98:99]
	v_add_u32_e32 v249, 0x400, v249
	s_waitcnt lgkmcnt(3)
	global_store_dwordx4 v249, v[56:59], s[98:99]
	v_add_u32_e32 v249, 0x400, v249
	s_waitcnt lgkmcnt(2)
	global_store_dwordx4 v249, v[60:63], s[98:99]
	v_add_u32_e32 v249, 0x400, v249
	s_waitcnt lgkmcnt(1)
	global_store_dwordx4 v249, v[64:67], s[98:99]
	v_add_u32_e32 v249, 0x400, v249
	s_waitcnt lgkmcnt(0)
	global_store_dwordx4 v249, v[68:71], s[98:99]
	v_mov_b32_e32 v0, v250
	v_mov_b32_e32 v4, v251
	s_cbranch_vccnz .LBB0_337
	v_and_b32_e32 v1, 64, v215
	v_add_u32_e32 v2, 64, v1
	v_xor_b32_e32 v1, 16, v215
	v_cmp_lt_i32_e32 vcc, v1, v2
	s_nop 1
	v_cndmask_b32_e32 v1, v215, v1, vcc
	v_lshlrev_b32_e32 v1, 2, v1
	ds_bpermute_b32 v3, v1, v0
	ds_bpermute_b32 v1, v1, v4
	s_waitcnt lgkmcnt(1)
	v_add_f32_e32 v0, v0, v3
	v_xor_b32_e32 v3, 8, v215
	v_cmp_lt_i32_e32 vcc, v3, v2
	s_waitcnt lgkmcnt(0)
	v_add_f32_e32 v1, v4, v1
	v_cndmask_b32_e32 v3, v215, v3, vcc
	v_lshlrev_b32_e32 v3, 2, v3
	ds_bpermute_b32 v4, v3, v0
	ds_bpermute_b32 v3, v3, v1
	s_waitcnt lgkmcnt(1)
	v_add_f32_e32 v0, v0, v4
	s_waitcnt lgkmcnt(0)
	v_add_f32_e32 v1, v1, v3
	v_xor_b32_e32 v3, 4, v215
	v_cmp_lt_i32_e32 vcc, v3, v2
	s_nop 1
	v_cndmask_b32_e32 v3, v215, v3, vcc
	v_lshlrev_b32_e32 v3, 2, v3
	ds_bpermute_b32 v4, v3, v0
	ds_bpermute_b32 v3, v3, v1
	s_waitcnt lgkmcnt(1)
	v_add_f32_e32 v0, v0, v4
	s_waitcnt lgkmcnt(0)
	v_add_f32_e32 v1, v1, v3
	v_xor_b32_e32 v3, 2, v215
	v_cmp_lt_i32_e32 vcc, v3, v2
	s_nop 1
	v_cndmask_b32_e32 v3, v215, v3, vcc
	v_lshlrev_b32_e32 v3, 2, v3
	ds_bpermute_b32 v4, v3, v0
	ds_bpermute_b32 v3, v3, v1
	s_waitcnt lgkmcnt(1)
	v_add_f32_e32 v0, v0, v4
	s_waitcnt lgkmcnt(0)
	v_add_f32_e32 v1, v1, v3
	v_xor_b32_e32 v3, 1, v215
	v_cmp_lt_i32_e32 vcc, v3, v2
	s_nop 1
	v_cndmask_b32_e32 v3, v215, v3, vcc
	v_lshlrev_b32_e32 v3, 2, v3
	ds_bpermute_b32 v4, v3, v0
	ds_bpermute_b32 v3, v3, v1
	s_waitcnt lgkmcnt(1)
	v_add_f32_e32 v0, v0, v4
	s_waitcnt lgkmcnt(0)
	v_add_f32_e32 v1, v1, v3
	v_xor_b32_e32 v3, 32, v215
	v_cmp_lt_i32_e32 vcc, v3, v2
	v_and_b32_e32 v4, 63, v176
	s_nop 0
	v_cndmask_b32_e32 v2, v215, v3, vcc
	v_lshlrev_b32_e32 v3, 2, v2
	ds_bpermute_b32 v2, v3, v0
	ds_bpermute_b32 v3, v3, v1
	v_cmp_eq_u32_e32 vcc, 0, v4
	s_and_saveexec_b64 s[8:9], vcc
	s_cbranch_execz .LBB0_336
	s_waitcnt lgkmcnt(1)
	v_max_f32_e32 v2, v2, v2
	v_max_f32_e32 v0, v0, v0
	s_and_b32 s56, s75, 32
	v_readlane_b32 s76, v248, 26
	s_waitcnt lgkmcnt(0)
	v_max_f32_e32 v3, v3, v3
	v_max_f32_e32 v1, v1, v1
	v_max_f32_e32 v0, v0, v2
	v_readlane_b32 s77, v248, 27
	s_add_u32 s76, s76, s56
	v_max_f32_e32 v1, v1, v3
	v_mul_f32_e32 v0, 0x3f828f5c, v0
	s_addc_u32 s77, s77, 0
	v_lshlrev_b32_e32 v2, 3, v134
	v_mul_f32_e32 v1, 0x3f828f5c, v1
	global_atomic_umax v2, v0, s[76:77]
	global_atomic_umax v2, v1, s[76:77] offset:4
